# phase-A prenorm: j=1..3 param loads hoisted above the wave reduction (same as phase H)
# speedup vs baseline: 1.0303x; 1.0014x over previous
; __device__ __forceinline__ unsigned pk2(float lo, float hi) { const f32x2 v = {lo, hi}; return __builtin_bit_cast(unsigned, __builtin_convertvector(v, bf16v2_t)); }
; __device__ __forceinline__ void prenorm_row(float* xr, const float* g, const float* shift, const float* scale, bf16_t* orow, int lane, const LAS unsigned char* tmap, const float* PB, int r) {
;     ...
; #pragma unroll
;     for (int j = 0; j < 4; ++j) s += (v[j].x * v[j].x + v[j].y * v[j].y) + (v[j].z * v[j].z + v[j].w * v[j].w);
;     const float rstd = rsqrtf(wave_sum(s) * (1.f / DM) + 1e-6f);
; #pragma unroll
;     for (int j = 0; j < 4; ++j) {
;         const f32x4 gg = ((const f32x4*)g)[lane + 64 * j], sh = ((const f32x4*)shift)[lane + 64 * j], sc = ((const f32x4*)scale)[lane + 64 * j];
;         const f32x4 y = v[j] * rstd * gg * (sc + 1.f) + sh;
;         u32x2 o; o.x = pk2(y.x, y.y); o.y = pk2(y.z, y.w);
;         ((u32x2*)orow)[lane + 64 * j] = o;
;     }
.LBB0_226:
	s_andn2_saveexec_b64 s[22:23], s[22:23]
	s_or_b64 exec, exec, s[22:23]
	v_cndmask_b32_e64 v21, v38, 8, s[42:43]
	v_mul_hi_i32_i24_e32 v39, 0x6000, v21
	v_mul_i32_i24_e32 v38, 0x6000, v21
	v_lshl_add_u64 v[52:53], v[22:23], 0, v[38:39]
	s_mov_b64 s[18:19], 0x1000
	v_lshl_add_u64 v[56:57], v[52:53], 0, s[18:19]
	v_lshl_add_u64 v[48:49], v[56:57], 0, v[0:1]
	global_load_dwordx4 v[38:41], v[28:29], off
	v_lshl_add_u64 v[58:59], v[52:53], 0, v[0:1]
	global_load_dwordx4 v[48:51], v[48:49], off
	s_waitcnt vmcnt(0)
	v_pk_mul_f32 v[60:61], v[12:13], v[12:13]
	global_load_dwordx4 v[52:55], v[58:59], off
	v_pk_mul_f32 v[62:63], v[10:11], v[10:11]
	v_pk_mul_f32 v[64:65], v[16:17], v[16:17]
	v_pk_mul_f32 v[66:67], v[14:15], v[14:15]
	s_waitcnt vmcnt(4)
	v_mul_f32_e32 v0, v6, v6
	v_pk_mov_b32 v[70:71], v[66:67], v[64:65] op_sel:[1,0]
	v_mov_b32_e32 v67, v65
	v_pk_mov_b32 v[64:65], v[62:63], v[60:61] op_sel:[1,0]
	v_mov_b32_e32 v63, v61
	v_mul_f32_e32 v68, v8, v8
	v_pk_add_f32 v[66:67], v[70:71], v[66:67]
	v_pk_add_f32 v[62:63], v[64:65], v[62:63]
	v_pk_fma_f32 v[60:61], v[6:7], v[6:7], v[0:1] op_sel_hi:[1,1,0]
	v_pk_fma_f32 v[68:69], v[8:9], v[8:9], v[68:69] op_sel_hi:[1,1,0]
	v_pk_add_f32 v[64:65], v[66:67], v[66:67] op_sel_hi:[0,1]
	v_pk_add_f32 v[62:63], v[62:63], v[62:63] op_sel_hi:[0,1]
	s_waitcnt vmcnt(3)
	v_mul_f32_e32 v60, v2, v2
	v_mul_f32_e32 v68, v3, v3
	v_mul_f32_e32 v64, v4, v4
	v_mul_f32_e32 v62, v5, v5
	v_pk_add_f32 v[60:61], v[60:61], v[68:69]
	v_pk_add_f32 v[62:63], v[64:65], v[62:63]
	s_mov_b32 s3, 0x800000
	v_pk_add_f32 v[60:61], v[60:61], v[62:63]
	v_mov_b32_e32 v33, v1
	v_add_f32_e32 v0, v60, v61
	ds_bpermute_b32 v21, v25, v0
	v_lshl_add_u64 v[60:61], v[18:19], 0, v[30:31]
	v_mov_b32_e32 v35, v1
	v_mov_b32_e32 v37, v1
	v_lshl_add_u64 v[184:185], v[56:57], 0, v[32:33]
	v_lshl_add_u64 v[186:187], v[56:57], 0, v[34:35]
	v_lshl_add_u64 v[188:189], v[56:57], 0, v[36:37]
	global_load_dwordx4 v[148:151], v[28:29], off offset:1024
	global_load_dwordx4 v[152:155], v[184:185], off
	global_load_dwordx4 v[156:159], v[58:59], off offset:1024
	global_load_dwordx4 v[160:163], v[28:29], off offset:2048
	global_load_dwordx4 v[164:167], v[186:187], off
	global_load_dwordx4 v[168:171], v[58:59], off offset:2048
	global_load_dwordx4 v[172:175], v[28:29], off offset:3072
	global_load_dwordx4 v[176:179], v[188:189], off
	global_load_dwordx4 v[180:183], v[58:59], off offset:3072
	v_add_u32_e32 v20, s8, v20
	s_waitcnt lgkmcnt(0)
	v_add_f32_e32 v0, v0, v21
	ds_bpermute_b32 v21, v42, v0
	v_add_u32_e32 v47, s2, v47
	v_lshl_add_u64 v[30:31], v[30:31], 0, s[14:15]
	s_waitcnt lgkmcnt(0)
	v_add_f32_e32 v0, v0, v21
	ds_bpermute_b32 v21, v43, v0
	s_waitcnt lgkmcnt(0)
	v_add_f32_e32 v0, v0, v21
	ds_bpermute_b32 v21, v44, v0
	s_waitcnt lgkmcnt(0)
	v_add_f32_e32 v0, v0, v21
	ds_bpermute_b32 v21, v45, v0
	s_waitcnt lgkmcnt(0)
	v_add_f32_e32 v0, v0, v21
	ds_bpermute_b32 v21, v46, v0
	s_waitcnt lgkmcnt(0)
	v_add_f32_e32 v0, v0, v21
	v_fmamk_f32 v0, v0, 0x3a800000, v219
	v_mul_f32_e32 v21, 0x4b800000, v0
	v_cmp_gt_f32_e32 vcc, s3, v0
	s_mov_b32 s3, 0x33f8000
	v_add_co_u32_e64 v60, s[42:43], s3, v60
	v_cndmask_b32_e32 v0, v0, v21, vcc
	v_rsq_f32_e32 v0, v0
	v_addc_co_u32_e64 v61, s[42:43], 0, v61, s[42:43]
	s_mov_b32 s3, 0x87ff
	v_mul_f32_e32 v21, 0x45800000, v0
	v_cndmask_b32_e32 v0, v0, v21, vcc
	v_pk_mul_f32 v[16:17], v[16:17], v[0:1] op_sel_hi:[1,0]
	v_pk_mul_f32 v[14:15], v[14:15], v[0:1] op_sel_hi:[1,0]
	s_waitcnt vmcnt(10)
	v_pk_mul_f32 v[16:17], v[40:41], v[16:17]
	v_pk_mul_f32 v[14:15], v[38:39], v[14:15]
	v_pk_add_f32 v[38:39], v[50:51], 1.0 op_sel_hi:[1,0]
	v_pk_add_f32 v[40:41], v[48:49], 1.0 op_sel_hi:[1,0]
	s_waitcnt vmcnt(9)
	v_pk_fma_f32 v[16:17], v[38:39], v[16:17], v[54:55]
	v_pk_fma_f32 v[14:15], v[40:41], v[14:15], v[52:53]
	s_nop 0
	v_cvt_pk_bf16_f32 v14, v14, v15
	v_cvt_pk_bf16_f32 v15, v16, v17
	global_store_dwordx2 v[60:61], v[14:15], off
	v_pk_mul_f32 v[12:13], v[12:13], v[0:1] op_sel_hi:[1,0]
	v_pk_mul_f32 v[10:11], v[10:11], v[0:1] op_sel_hi:[1,0]
	v_pk_mul_f32 v[8:9], v[8:9], v[0:1] op_sel_hi:[1,0]
	v_pk_mul_f32 v[6:7], v[6:7], v[0:1] op_sel_hi:[1,0]
	v_pk_mul_f32 v[4:5], v[4:5], v[0:1] op_sel_hi:[1,0]
	v_pk_mul_f32 v[2:3], v[2:3], v[0:1] op_sel_hi:[1,0]
	v_cmp_lt_i32_e32 vcc, s3, v20
	s_or_b64 s[16:17], vcc, s[16:17]
	s_waitcnt vmcnt(9)
	v_pk_mul_f32 v[10:11], v[148:149], v[10:11]
	v_pk_mul_f32 v[12:13], v[150:151], v[12:13]
	s_waitcnt vmcnt(8)
	v_pk_add_f32 v[14:15], v[154:155], 1.0 op_sel_hi:[1,0]
	v_pk_add_f32 v[16:17], v[152:153], 1.0 op_sel_hi:[1,0]
	s_waitcnt vmcnt(7)
	v_pk_fma_f32 v[12:13], v[14:15], v[12:13], v[158:159]
	v_pk_fma_f32 v[10:11], v[16:17], v[10:11], v[156:157]
	s_nop 0
	v_cvt_pk_bf16_f32 v10, v10, v11
	v_cvt_pk_bf16_f32 v11, v12, v13
	global_store_dwordx2 v[60:61], v[10:11], off offset:512
	s_waitcnt vmcnt(7)
	v_pk_mul_f32 v[6:7], v[160:161], v[6:7]
	v_pk_mul_f32 v[8:9], v[162:163], v[8:9]
	s_waitcnt vmcnt(6)
	v_pk_add_f32 v[10:11], v[166:167], 1.0 op_sel_hi:[1,0]
	v_pk_add_f32 v[12:13], v[164:165], 1.0 op_sel_hi:[1,0]
	s_waitcnt vmcnt(5)
	v_pk_fma_f32 v[8:9], v[10:11], v[8:9], v[170:171]
	v_pk_fma_f32 v[6:7], v[12:13], v[6:7], v[168:169]
	s_nop 0
	v_cvt_pk_bf16_f32 v6, v6, v7
	v_cvt_pk_bf16_f32 v7, v8, v9
	global_store_dwordx2 v[60:61], v[6:7], off offset:1024
	s_waitcnt vmcnt(5)
	v_pk_mul_f32 v[2:3], v[172:173], v[2:3]
	v_pk_mul_f32 v[4:5], v[174:175], v[4:5]
	s_waitcnt vmcnt(4)
	v_pk_add_f32 v[6:7], v[178:179], 1.0 op_sel_hi:[1,0]
	v_pk_add_f32 v[8:9], v[176:177], 1.0 op_sel_hi:[1,0]
	s_waitcnt vmcnt(3)
	v_pk_fma_f32 v[4:5], v[6:7], v[4:5], v[182:183]
	v_pk_fma_f32 v[2:3], v[8:9], v[2:3], v[180:181]
	s_nop 0
	v_cvt_pk_bf16_f32 v2, v2, v3
	v_cvt_pk_bf16_f32 v3, v4, v5
	global_store_dwordx2 v[60:61], v[2:3], off offset:1536
	s_andn2_b64 exec, exec, s[16:17]
	s_cbranch_execz .LBB0_238
